# hand-written epilogue for the plain (V / z) tiles of the RoPE GEMM instance: 16 x (4 cvt + one 16-byte store) with scalar pointer steps instead of the compiler's per-call branch + address ladder
# speedup vs baseline: 1.0055x; 1.0055x over previous
; #define GM_WAIT_V(n) asm volatile("s_waitcnt vmcnt(" #n ")" ::: "memory")
; #define GM_WAIT_L(n) asm volatile("s_waitcnt lgkmcnt(" #n ")" ::: "memory")
; #define GM_BAR __builtin_amdgcn_s_barrier()
; #define GM_SCHED __builtin_amdgcn_sched_barrier(0)
; #define GM_LDA(dst, b, h) _Pragma("unroll") for (int m = 0; m < 4; ++m) _Pragma("unroll") for (int k = 0; k < 2; ++k) \
;         dst[m][k] = *(const LAS bf16x8*)(GM_SA(b, h) + aoff + (m * 2 + k) * 1024)
; #define GM_LDB(dst, b, h) _Pragma("unroll") for (int n = 0; n < 2; ++n) _Pragma("unroll") for (int k = 0; k < 2; ++k) \
;         dst[n][k] = *(const LAS bf16x8*)(GM_SB(b, h) + boff + (n * 2 + k) * 1024)
; #define GM_MMA(ai, bj, At, Bv) do { __builtin_amdgcn_s_setprio(1); \
;         _Pragma("unroll") for (int m = 0; m < 4; ++m) _Pragma("unroll") for (int n = 0; n < 2; ++n) _Pragma("unroll") for (int k = 0; k < 2; ++k) \
;             acc[ai][bj][m][n] = __builtin_amdgcn_mfma_f32_16x16x32_bf16(Bv[n][k], At[m][k], acc[ai][bj][m][n], 0, 0, 0); \
;         __builtin_amdgcn_s_setprio(0); } while (0)
; template <class Epi>
; __device__ __forceinline__ void gemm_phase(const bf16_t* __restrict__ A, const bf16_t* __restrict__ Bt, int M, int N, LAS unsigned char* lds, const Epi& epi, int vcu) {
;     ...
;         for (int t = 0; t < NT; t += 2) {
;             const bool lastk = (t + 2 >= NT);
;             const int prow = lastk ? nrow : brow, pcol = lastk ? ncol : bcol, k2 = lastk ? 0 : t + 2, k3 = lastk ? 1 : t + 3;
;             GM_LDB(B0, 0, 0); GM_SCHED; GM_LDA(At, 0, 0); GM_STAGE(GM_SA(1, 1), A, brow + HALF, t + 1);
;             GM_WAIT_L(8); GM_BAR; GM_WAIT_L(0); GM_MMA(0, 0, At, B0); GM_BAR; GM_SCHED;
;             GM_LDB(B1, 0, 1); GM_STAGE(GM_SB(0, 0), Bt, pcol, k2);
;             GM_BAR; GM_WAIT_L(0); GM_MMA(0, 1, At, B1); GM_BAR;
;             GM_LDA(At, 0, 1); GM_STAGE(GM_SA(0, 0), A, prow, k2);
;             GM_BAR; GM_WAIT_L(0); GM_MMA(1, 0, At, B0); GM_BAR; GM_SCHED;
;             GM_STAGE(GM_SB(0, 1), Bt, pcol + HALF, k2);
;             GM_WAIT_V(6); GM_BAR; GM_MMA(1, 1, At, B1); GM_BAR;
;             GM_LDB(B0, 1, 0); GM_SCHED; GM_LDA(At, 1, 0); GM_STAGE(GM_SA(0, 1), A, prow + HALF, k2);
;             GM_WAIT_L(8); GM_BAR; GM_WAIT_L(0); GM_MMA(0, 0, At, B0); GM_BAR; GM_SCHED;
.LBB0_255:
	s_add_i32 s43, s43, 2
	v_add_u32_e32 v149, s88, v141
	s_cmp_gt_u32 s43, 13
	ds_read_b128 v[150:153], v149
	ds_read_b128 v[154:157], v149 offset:1024
	ds_read_b128 v[158:161], v149 offset:2048
	ds_read_b128 v[162:165], v149 offset:3072
	s_cselect_b64 s[54:55], -1, 0
	s_and_b64 s[54:55], s[54:55], exec
	s_cselect_b32 s54, 64, s45
	s_sub_i32 s10, s45, 64
	s_cmp_gt_u32 s43, 13
	s_cselect_b64 s[56:57], -1, 0
	s_and_b64 vcc, s[56:57], exec
	s_cselect_b32 s56, s5, s42
	s_cselect_b32 s58, s78, s44
	s_cselect_b32 s96, 0, s10
	v_add_u32_e32 v199, 0xc000, v133
	v_mov_b32_e32 v149, v1
	v_mov_b32_e32 v198, v130
	v_readfirstlane_b32 s10, v199
	ds_read_b128 v[166:169], v148
	ds_read_b128 v[170:173], v148 offset:1024
	ds_read_b128 v[174:177], v148 offset:2048
	ds_read_b128 v[178:181], v148 offset:3072
	ds_read_b128 v[182:185], v148 offset:4096
	ds_read_b128 v[186:189], v148 offset:5120
	ds_read_b128 v[190:193], v148 offset:6144
	ds_read_b128 v[194:197], v148 offset:7168
	s_mov_b32 m0, s10
	s_nop 0
	global_load_lds_dwordx4 v149, s[52:53]
	v_add_u32_e32 v149, 0xe000, v133
	s_nop 0
	v_readfirstlane_b32 s10, v149
	s_mov_b32 m0, s10
	s_nop 0
	global_load_lds_dwordx4 v198, s[52:53]
	s_waitcnt lgkmcnt(8)
	s_barrier
	s_waitcnt lgkmcnt(0)
	s_setprio 1
	s_waitcnt lgkmcnt(0)
	v_mfma_f32_16x16x32_bf16 v[126:129], v[150:153], v[166:169], v[126:129]
	v_mfma_f32_16x16x32_bf16 v[122:125], v[158:161], v[166:169], v[122:125]
	v_mfma_f32_16x16x32_bf16 v[110:113], v[150:153], v[174:177], v[110:113]
	v_mfma_f32_16x16x32_bf16 v[106:109], v[158:161], v[174:177], v[106:109]
	v_mfma_f32_16x16x32_bf16 v[94:97], v[150:153], v[182:185], v[94:97]
	v_mfma_f32_16x16x32_bf16 v[90:93], v[158:161], v[182:185], v[90:93]
	v_mfma_f32_16x16x32_bf16 v[78:81], v[150:153], v[190:193], v[78:81]
	v_mfma_f32_16x16x32_bf16 v[74:77], v[158:161], v[190:193], v[74:77]
	v_mfma_f32_16x16x32_bf16 v[126:129], v[154:157], v[170:173], v[126:129]
	v_mfma_f32_16x16x32_bf16 v[122:125], v[162:165], v[170:173], v[122:125]
	v_mfma_f32_16x16x32_bf16 v[110:113], v[154:157], v[178:181], v[110:113]
	v_mfma_f32_16x16x32_bf16 v[106:109], v[162:165], v[178:181], v[106:109]
	v_mfma_f32_16x16x32_bf16 v[94:97], v[154:157], v[186:189], v[94:97]
	v_mfma_f32_16x16x32_bf16 v[90:93], v[162:165], v[186:189], v[90:93]
	v_mfma_f32_16x16x32_bf16 v[78:81], v[154:157], v[194:197], v[78:81]
	v_mfma_f32_16x16x32_bf16 v[74:77], v[162:165], v[194:197], v[74:77]
	s_setprio 0
	s_barrier
	s_ashr_i32 s59, s58, 31
	s_lshl_b64 s[58:59], s[58:59], 11
	s_add_u32 s2, s51, s58
	s_addc_u32 s83, s34, s59
	s_lshl_b64 s[58:59], s[96:97], 1
	v_add_u32_e32 v149, s89, v141
	s_add_u32 s10, s2, s58
	v_readfirstlane_b32 s55, v131
	ds_read_b128 v[198:201], v149
	ds_read_b128 v[202:205], v149 offset:1024
	ds_read_b128 v[212:215], v149 offset:2048
	ds_read_b128 v[216:219], v149 offset:3072
	s_addc_u32 s11, s83, s59
	v_mov_b32_e32 v149, v1
	v_mov_b32_e32 v208, v130
	s_mov_b32 m0, s55
	v_readfirstlane_b32 s55, v132
	s_nop 0
	global_load_lds_dwordx4 v149, s[10:11]
	s_mov_b32 m0, s55
	s_nop 0
	global_load_lds_dwordx4 v208, s[10:11]
	s_barrier
	s_waitcnt lgkmcnt(0)
	s_setprio 1
	s_waitcnt lgkmcnt(0)
	v_mfma_f32_16x16x32_bf16 v[118:121], v[198:201], v[166:169], v[118:121]
	v_mfma_f32_16x16x32_bf16 v[114:117], v[212:215], v[166:169], v[114:117]
	v_mfma_f32_16x16x32_bf16 v[102:105], v[198:201], v[174:177], v[102:105]
	v_mfma_f32_16x16x32_bf16 v[98:101], v[212:215], v[174:177], v[98:101]
	v_mfma_f32_16x16x32_bf16 v[86:89], v[198:201], v[182:185], v[86:89]
	v_mfma_f32_16x16x32_bf16 v[82:85], v[212:215], v[182:185], v[82:85]
	v_mfma_f32_16x16x32_bf16 v[70:73], v[198:201], v[190:193], v[70:73]
	v_mfma_f32_16x16x32_bf16 v[66:69], v[212:215], v[190:193], v[66:69]
	v_mfma_f32_16x16x32_bf16 v[118:121], v[202:205], v[170:173], v[118:121]
	v_mfma_f32_16x16x32_bf16 v[114:117], v[216:219], v[170:173], v[114:117]
	v_mfma_f32_16x16x32_bf16 v[102:105], v[202:205], v[178:181], v[102:105]
	v_mfma_f32_16x16x32_bf16 v[98:101], v[216:219], v[178:181], v[98:101]
	v_mfma_f32_16x16x32_bf16 v[86:89], v[202:205], v[186:189], v[86:89]
	v_mfma_f32_16x16x32_bf16 v[82:85], v[216:219], v[186:189], v[82:85]
	v_mfma_f32_16x16x32_bf16 v[70:73], v[202:205], v[194:197], v[70:73]
	v_mfma_f32_16x16x32_bf16 v[66:69], v[216:219], v[194:197], v[66:69]
	s_setprio 0
	s_ashr_i32 s57, s56, 31
	s_lshl_b64 s[10:11], s[56:57], 11
	s_add_u32 s96, s14, s10
	s_addc_u32 s36, s15, s11
	s_add_u32 s10, s96, s58
	v_readfirstlane_b32 s55, v133
	s_addc_u32 s11, s36, s59
	v_mov_b32_e32 v149, v1
	v_mov_b32_e32 v208, v130
	s_mov_b32 m0, s55
	v_readfirstlane_b32 s55, v134
	s_barrier
	ds_read_b128 v[166:169], v148 offset:16384
	ds_read_b128 v[170:173], v148 offset:17408
	ds_read_b128 v[174:177], v148 offset:18432
	ds_read_b128 v[178:181], v148 offset:19456
	ds_read_b128 v[182:185], v148 offset:20480
	ds_read_b128 v[186:189], v148 offset:21504
	ds_read_b128 v[190:193], v148 offset:22528
	ds_read_b128 v[194:197], v148 offset:23552
	s_nop 0
	global_load_lds_dwordx4 v149, s[10:11]
	s_mov_b32 m0, s55
	s_nop 0
	global_load_lds_dwordx4 v208, s[10:11]
	s_barrier
; #define GM_WAIT_V(n) asm volatile("s_waitcnt vmcnt(" #n ")" ::: "memory")
; #define GM_WAIT_L(n) asm volatile("s_waitcnt lgkmcnt(" #n ")" ::: "memory")
; #define GM_BAR __builtin_amdgcn_s_barrier()
; #define GM_SCHED __builtin_amdgcn_sched_barrier(0)
; #define GM_LDA(dst, b, h) _Pragma("unroll") for (int m = 0; m < 4; ++m) _Pragma("unroll") for (int k = 0; k < 2; ++k) \
;         dst[m][k] = *(const LAS bf16x8*)(GM_SA(b, h) + aoff + (m * 2 + k) * 1024)
; #define GM_LDB(dst, b, h) _Pragma("unroll") for (int n = 0; n < 2; ++n) _Pragma("unroll") for (int k = 0; k < 2; ++k) \
;         dst[n][k] = *(const LAS bf16x8*)(GM_SB(b, h) + boff + (n * 2 + k) * 1024)
; #define GM_MMA(ai, bj, At, Bv) do { __builtin_amdgcn_s_setprio(1); \
;         _Pragma("unroll") for (int m = 0; m < 4; ++m) _Pragma("unroll") for (int n = 0; n < 2; ++n) _Pragma("unroll") for (int k = 0; k < 2; ++k) \
;             acc[ai][bj][m][n] = __builtin_amdgcn_mfma_f32_16x16x32_bf16(Bv[n][k], At[m][k], acc[ai][bj][m][n], 0, 0, 0); \
;         __builtin_amdgcn_s_setprio(0); } while (0)
; template <class Epi>
; __device__ __forceinline__ void gemm_phase(const bf16_t* __restrict__ A, const bf16_t* __restrict__ Bt, int M, int N, LAS unsigned char* lds, const Epi& epi, int vcu) {
;     ...
;             GM_BAR; GM_WAIT_L(0); GM_MMA(1, 0, At, B0); GM_BAR; GM_SCHED;
;             GM_STAGE(GM_SB(0, 1), Bt, pcol + HALF, k2);
;             GM_WAIT_V(6); GM_BAR; GM_MMA(1, 1, At, B1); GM_BAR;
;             GM_LDB(B0, 1, 0); GM_SCHED; GM_LDA(At, 1, 0); GM_STAGE(GM_SA(0, 1), A, prow + HALF, k2);
;             GM_WAIT_L(8); GM_BAR; GM_WAIT_L(0); GM_MMA(0, 0, At, B0); GM_BAR; GM_SCHED;
;             GM_LDB(B1, 1, 1); GM_STAGE(GM_SB(1, 0), Bt, pcol, k3);
	s_waitcnt lgkmcnt(0)
	s_setprio 1
	s_waitcnt lgkmcnt(0)
	v_mfma_f32_16x16x32_bf16 v[62:65], v[150:153], v[166:169], v[62:65]
	v_mfma_f32_16x16x32_bf16 v[58:61], v[158:161], v[166:169], v[58:61]
	v_mfma_f32_16x16x32_bf16 v[46:49], v[150:153], v[174:177], v[46:49]
	v_mfma_f32_16x16x32_bf16 v[42:45], v[158:161], v[174:177], v[42:45]
	v_mfma_f32_16x16x32_bf16 v[30:33], v[150:153], v[182:185], v[30:33]
	v_mfma_f32_16x16x32_bf16 v[26:29], v[158:161], v[182:185], v[26:29]
	v_mfma_f32_16x16x32_bf16 v[14:17], v[150:153], v[190:193], v[14:17]
	v_mfma_f32_16x16x32_bf16 v[10:13], v[158:161], v[190:193], v[10:13]
	v_mfma_f32_16x16x32_bf16 v[62:65], v[154:157], v[170:173], v[62:65]
	v_mfma_f32_16x16x32_bf16 v[58:61], v[162:165], v[170:173], v[58:61]
	v_mfma_f32_16x16x32_bf16 v[46:49], v[154:157], v[178:181], v[46:49]
	v_mfma_f32_16x16x32_bf16 v[42:45], v[162:165], v[178:181], v[42:45]
	v_mfma_f32_16x16x32_bf16 v[30:33], v[154:157], v[186:189], v[30:33]
	v_mfma_f32_16x16x32_bf16 v[26:29], v[162:165], v[186:189], v[26:29]
	v_mfma_f32_16x16x32_bf16 v[14:17], v[154:157], v[194:197], v[14:17]
	v_mfma_f32_16x16x32_bf16 v[10:13], v[162:165], v[194:197], v[10:13]
	s_setprio 0
	s_barrier
	s_add_u32 s35, s2, 0x40000
	s_addc_u32 s70, s83, 0
	s_add_u32 s56, s35, s58
	v_readfirstlane_b32 s55, v135
	s_addc_u32 s57, s70, s59
	v_mov_b32_e32 v149, v1
	v_mov_b32_e32 v150, v130
	s_mov_b32 m0, s55
	v_readfirstlane_b32 s55, v136
	s_nop 0
	global_load_lds_dwordx4 v149, s[56:57]
	s_mov_b32 m0, s55
	s_nop 0
	global_load_lds_dwordx4 v150, s[56:57]
	s_waitcnt vmcnt(6)
	s_barrier
	s_setprio 1
	v_mfma_f32_16x16x32_bf16 v[54:57], v[198:201], v[166:169], v[54:57]
	v_mfma_f32_16x16x32_bf16 v[50:53], v[212:215], v[166:169], v[50:53]
	v_mfma_f32_16x16x32_bf16 v[38:41], v[198:201], v[174:177], v[38:41]
	v_mfma_f32_16x16x32_bf16 v[34:37], v[212:215], v[174:177], v[34:37]
	v_mfma_f32_16x16x32_bf16 v[22:25], v[198:201], v[182:185], v[22:25]
	v_mfma_f32_16x16x32_bf16 v[18:21], v[212:215], v[182:185], v[18:21]
	v_mfma_f32_16x16x32_bf16 v[6:9], v[198:201], v[190:193], v[6:9]
	v_mfma_f32_16x16x32_bf16 v[2:5], v[212:215], v[190:193], v[2:5]
	v_mfma_f32_16x16x32_bf16 v[54:57], v[202:205], v[170:173], v[54:57]
	v_mfma_f32_16x16x32_bf16 v[50:53], v[216:219], v[170:173], v[50:53]
	v_mfma_f32_16x16x32_bf16 v[38:41], v[202:205], v[178:181], v[38:41]
	v_mfma_f32_16x16x32_bf16 v[34:37], v[216:219], v[178:181], v[34:37]
	v_mfma_f32_16x16x32_bf16 v[22:25], v[202:205], v[186:189], v[22:25]
	v_mfma_f32_16x16x32_bf16 v[18:21], v[216:219], v[186:189], v[18:21]
	v_mfma_f32_16x16x32_bf16 v[6:9], v[202:205], v[194:197], v[6:9]
	v_mfma_f32_16x16x32_bf16 v[2:5], v[216:219], v[194:197], v[2:5]
	s_setprio 0
	v_add_u32_e32 v149, s16, v141
	s_barrier
	ds_read_b128 v[150:153], v149
	ds_read_b128 v[154:157], v149 offset:1024
	ds_read_b128 v[158:161], v149 offset:2048
	ds_read_b128 v[162:165], v149 offset:3072
	s_add_u32 s10, s10, 0x40000
	v_readfirstlane_b32 s55, v137
	s_addc_u32 s11, s11, 0
	v_mov_b32_e32 v149, v1
	v_mov_b32_e32 v198, v130
	s_mov_b32 m0, s55
	v_readfirstlane_b32 s55, v138
	ds_read_b128 v[166:169], v148 offset:32768
	ds_read_b128 v[170:173], v148 offset:33792
	ds_read_b128 v[174:177], v148 offset:34816
	ds_read_b128 v[178:181], v148 offset:35840
	ds_read_b128 v[182:185], v148 offset:36864
	ds_read_b128 v[186:189], v148 offset:37888
	ds_read_b128 v[190:193], v148 offset:38912
	ds_read_b128 v[194:197], v148 offset:39936
	s_nop 0
	global_load_lds_dwordx4 v149, s[10:11]
	s_mov_b32 m0, s55
	s_nop 0
	global_load_lds_dwordx4 v198, s[10:11]
	s_waitcnt lgkmcnt(8)
	s_barrier
	s_waitcnt lgkmcnt(0)
	s_setprio 1
	s_waitcnt lgkmcnt(0)
	v_mfma_f32_16x16x32_bf16 v[126:129], v[150:153], v[166:169], v[126:129]
	v_mfma_f32_16x16x32_bf16 v[122:125], v[158:161], v[166:169], v[122:125]
	v_mfma_f32_16x16x32_bf16 v[110:113], v[150:153], v[174:177], v[110:113]
	v_mfma_f32_16x16x32_bf16 v[106:109], v[158:161], v[174:177], v[106:109]
	v_mfma_f32_16x16x32_bf16 v[94:97], v[150:153], v[182:185], v[94:97]
	v_mfma_f32_16x16x32_bf16 v[90:93], v[158:161], v[182:185], v[90:93]
	v_mfma_f32_16x16x32_bf16 v[78:81], v[150:153], v[190:193], v[78:81]
	v_mfma_f32_16x16x32_bf16 v[74:77], v[158:161], v[190:193], v[74:77]
	v_mfma_f32_16x16x32_bf16 v[126:129], v[154:157], v[170:173], v[126:129]
	v_mfma_f32_16x16x32_bf16 v[122:125], v[162:165], v[170:173], v[122:125]
	v_mfma_f32_16x16x32_bf16 v[110:113], v[154:157], v[178:181], v[110:113]
	v_mfma_f32_16x16x32_bf16 v[106:109], v[162:165], v[178:181], v[106:109]
	v_mfma_f32_16x16x32_bf16 v[94:97], v[154:157], v[186:189], v[94:97]
	v_mfma_f32_16x16x32_bf16 v[90:93], v[162:165], v[186:189], v[90:93]
	v_mfma_f32_16x16x32_bf16 v[78:81], v[154:157], v[194:197], v[78:81]
	v_mfma_f32_16x16x32_bf16 v[74:77], v[162:165], v[194:197], v[74:77]
	s_setprio 0
	s_barrier
	s_mov_b32 s55, s97
	s_lshl_b64 s[10:11], s[54:55], 1
	v_add_u32_e32 v149, s17, v141
	s_add_u32 s54, s2, s10
	v_readfirstlane_b32 s2, v142
	ds_read_b128 v[198:201], v149
	ds_read_b128 v[202:205], v149 offset:1024
	ds_read_b128 v[212:215], v149 offset:2048
	ds_read_b128 v[216:219], v149 offset:3072
	s_addc_u32 s55, s83, s11
	v_mov_b32_e32 v149, v1
	v_mov_b32_e32 v208, v130
	s_mov_b32 m0, s2
	v_readfirstlane_b32 s2, v143
	s_nop 0
	global_load_lds_dwordx4 v149, s[54:55]
	s_mov_b32 m0, s2
	s_nop 0
	global_load_lds_dwordx4 v208, s[54:55]
	s_barrier
; __device__ __forceinline__ unsigned pk_bf16(float lo, float hi) { const f32x2 v = {lo, hi}; const bf16v2 b = __builtin_convertvector(v, bf16v2); return __builtin_bit_cast(unsigned, b); }
; #define GM_WAIT_V(n) asm volatile("s_waitcnt vmcnt(" #n ")" ::: "memory")
; #define GM_WAIT_L(n) asm volatile("s_waitcnt lgkmcnt(" #n ")" ::: "memory")
; #define GM_BAR __builtin_amdgcn_s_barrier()
; #define GM_SCHED __builtin_amdgcn_sched_barrier(0)
; #define GM_LDA(dst, b, h) _Pragma("unroll") for (int m = 0; m < 4; ++m) _Pragma("unroll") for (int k = 0; k < 2; ++k) \
;         dst[m][k] = *(const LAS bf16x8*)(GM_SA(b, h) + aoff + (m * 2 + k) * 1024)
; template <class Epi>
; __device__ __forceinline__ void gemm_phase(const bf16_t* __restrict__ A, const bf16_t* __restrict__ Bt, int M, int N, LAS unsigned char* lds, const Epi& epi, int vcu) {
;     ...
;             GM_BAR; GM_WAIT_L(0); GM_MMA(0, 1, At, B1); GM_BAR;
;             GM_LDA(At, 1, 1); GM_STAGE(GM_SA(1, 0), A, prow, k3);
;             GM_BAR; GM_WAIT_L(0); GM_MMA(1, 0, At, B0); GM_BAR; GM_SCHED;
;             GM_STAGE(GM_SB(1, 1), Bt, pcol + HALF, k3);
;             GM_WAIT_V(6); GM_BAR; GM_MMA(1, 1, At, B1); GM_BAR;
;     __device__ __forceinline__ void operator()(int row, int G, int fq, f32x4 v0, f32x4 v1) const {
;     ...
;         if (col32 < rope_end) {
;             const int half = hd >> 1, hb = col32 & ~(hd - 1), d0 = ((col32 & (hd - 1)) >> 5) * 16 + fq * 4, pos = row & (SEQ - 1);
;             const unsigned to = (unsigned)(pos * half + d0);
;             const f32x4 c = *(const f32x4*)(cosT + to), s = *(const f32x4*)(sinT + to);
;             const f32x4 o1 = v0 * c - v1 * s, o2 = v1 * c + v0 * s;
;             u32x2 w1, w2; w1.x = pk_bf16(o1[0], o1[1]); w1.y = pk_bf16(o1[2], o1[3]); w2.x = pk_bf16(o2[0], o2[1]); w2.y = pk_bf16(o2[2], o2[3]);
;             *(u32x2*)(out + (ro + (unsigned)(hb + d0))) = w1; *(u32x2*)(out + (ro + (unsigned)(hb + half + d0))) = w2;
;         } else {
;             u32x4 w; w.x = pk_bf16(v0[0], v0[1]); w.y = pk_bf16(v0[2], v0[3]); w.z = pk_bf16(v1[0], v1[1]); w.w = pk_bf16(v1[2], v1[3]);
;             *(u32x4*)(out + (ro + (unsigned)(col32 + 8 * fq))) = w;
	s_waitcnt lgkmcnt(0)
	s_setprio 1
	s_waitcnt lgkmcnt(0)
	v_mfma_f32_16x16x32_bf16 v[118:121], v[198:201], v[166:169], v[118:121]
	v_mfma_f32_16x16x32_bf16 v[114:117], v[212:215], v[166:169], v[114:117]
	v_mfma_f32_16x16x32_bf16 v[102:105], v[198:201], v[174:177], v[102:105]
	v_mfma_f32_16x16x32_bf16 v[98:101], v[212:215], v[174:177], v[98:101]
	v_mfma_f32_16x16x32_bf16 v[86:89], v[198:201], v[182:185], v[86:89]
	v_mfma_f32_16x16x32_bf16 v[82:85], v[212:215], v[182:185], v[82:85]
	v_mfma_f32_16x16x32_bf16 v[70:73], v[198:201], v[190:193], v[70:73]
	v_mfma_f32_16x16x32_bf16 v[66:69], v[212:215], v[190:193], v[66:69]
	v_mfma_f32_16x16x32_bf16 v[118:121], v[202:205], v[170:173], v[118:121]
	v_mfma_f32_16x16x32_bf16 v[114:117], v[216:219], v[170:173], v[114:117]
	v_mfma_f32_16x16x32_bf16 v[102:105], v[202:205], v[178:181], v[102:105]
	v_mfma_f32_16x16x32_bf16 v[98:101], v[216:219], v[178:181], v[98:101]
	v_mfma_f32_16x16x32_bf16 v[86:89], v[202:205], v[186:189], v[86:89]
	v_mfma_f32_16x16x32_bf16 v[82:85], v[216:219], v[186:189], v[82:85]
	v_mfma_f32_16x16x32_bf16 v[70:73], v[202:205], v[194:197], v[70:73]
	v_mfma_f32_16x16x32_bf16 v[66:69], v[216:219], v[194:197], v[66:69]
	s_setprio 0
	s_add_u32 s54, s96, s10
	v_readfirstlane_b32 s2, v144
	s_addc_u32 s55, s36, s11
	v_mov_b32_e32 v149, v1
	v_mov_b32_e32 v208, v130
	s_mov_b32 m0, s2
	v_readfirstlane_b32 s2, v145
	s_barrier
	ds_read_b128 v[166:169], v148 offset:49152
	ds_read_b128 v[170:173], v148 offset:50176
	ds_read_b128 v[174:177], v148 offset:51200
	ds_read_b128 v[178:181], v148 offset:52224
	ds_read_b128 v[182:185], v148 offset:53248
	ds_read_b128 v[186:189], v148 offset:54272
	ds_read_b128 v[190:193], v148 offset:55296
	ds_read_b128 v[194:197], v148 offset:56320
	s_nop 0
	global_load_lds_dwordx4 v149, s[54:55]
	s_mov_b32 m0, s2
	s_nop 0
	global_load_lds_dwordx4 v208, s[54:55]
	s_barrier
	s_waitcnt lgkmcnt(0)
	s_setprio 1
	s_waitcnt lgkmcnt(0)
	v_mfma_f32_16x16x32_bf16 v[62:65], v[150:153], v[166:169], v[62:65]
	v_mfma_f32_16x16x32_bf16 v[58:61], v[158:161], v[166:169], v[58:61]
	v_mfma_f32_16x16x32_bf16 v[46:49], v[150:153], v[174:177], v[46:49]
	v_mfma_f32_16x16x32_bf16 v[42:45], v[158:161], v[174:177], v[42:45]
	v_mfma_f32_16x16x32_bf16 v[30:33], v[150:153], v[182:185], v[30:33]
	v_mfma_f32_16x16x32_bf16 v[26:29], v[158:161], v[182:185], v[26:29]
	v_mfma_f32_16x16x32_bf16 v[14:17], v[150:153], v[190:193], v[14:17]
	v_mfma_f32_16x16x32_bf16 v[10:13], v[158:161], v[190:193], v[10:13]
	v_mfma_f32_16x16x32_bf16 v[62:65], v[154:157], v[170:173], v[62:65]
	v_mfma_f32_16x16x32_bf16 v[58:61], v[162:165], v[170:173], v[58:61]
	v_mfma_f32_16x16x32_bf16 v[46:49], v[154:157], v[178:181], v[46:49]
	v_mfma_f32_16x16x32_bf16 v[42:45], v[162:165], v[178:181], v[42:45]
	v_mfma_f32_16x16x32_bf16 v[30:33], v[154:157], v[186:189], v[30:33]
	v_mfma_f32_16x16x32_bf16 v[26:29], v[162:165], v[186:189], v[26:29]
	v_mfma_f32_16x16x32_bf16 v[14:17], v[154:157], v[194:197], v[14:17]
	v_mfma_f32_16x16x32_bf16 v[10:13], v[162:165], v[194:197], v[10:13]
	s_setprio 0
	s_barrier
	s_add_u32 s10, s35, s10
	v_readfirstlane_b32 s2, v146
	s_addc_u32 s11, s70, s11
	v_mov_b32_e32 v149, v1
	v_mov_b32_e32 v150, v130
	s_mov_b32 m0, s2
	v_readfirstlane_b32 s2, v147
	s_nop 0
	global_load_lds_dwordx4 v149, s[10:11]
	s_mov_b32 m0, s2
	s_nop 0
	global_load_lds_dwordx4 v150, s[10:11]
	s_waitcnt vmcnt(6)
	s_barrier
	s_setprio 1
	v_mfma_f32_16x16x32_bf16 v[54:57], v[198:201], v[166:169], v[54:57]
	v_mfma_f32_16x16x32_bf16 v[50:53], v[212:215], v[166:169], v[50:53]
	v_mfma_f32_16x16x32_bf16 v[38:41], v[198:201], v[174:177], v[38:41]
	v_mfma_f32_16x16x32_bf16 v[34:37], v[212:215], v[174:177], v[34:37]
	v_mfma_f32_16x16x32_bf16 v[22:25], v[198:201], v[182:185], v[22:25]
	v_mfma_f32_16x16x32_bf16 v[18:21], v[212:215], v[182:185], v[18:21]
	v_mfma_f32_16x16x32_bf16 v[6:9], v[198:201], v[190:193], v[6:9]
	v_mfma_f32_16x16x32_bf16 v[2:5], v[212:215], v[190:193], v[2:5]
	v_mfma_f32_16x16x32_bf16 v[54:57], v[202:205], v[170:173], v[54:57]
	v_mfma_f32_16x16x32_bf16 v[50:53], v[216:219], v[170:173], v[50:53]
	v_mfma_f32_16x16x32_bf16 v[38:41], v[202:205], v[178:181], v[38:41]
	v_mfma_f32_16x16x32_bf16 v[34:37], v[216:219], v[178:181], v[34:37]
	v_mfma_f32_16x16x32_bf16 v[22:25], v[202:205], v[186:189], v[22:25]
	v_mfma_f32_16x16x32_bf16 v[18:21], v[216:219], v[186:189], v[18:21]
	v_mfma_f32_16x16x32_bf16 v[6:9], v[202:205], v[194:197], v[6:9]
	v_mfma_f32_16x16x32_bf16 v[2:5], v[216:219], v[194:197], v[2:5]
	s_setprio 0
	s_addk_i32 s45, 0x80
	s_add_u32 s52, s52, 0x100
	s_addc_u32 s53, s53, 0
	s_barrier
	s_cbranch_vccz .LBB0_255
	s_cmp_lt_i32 s44, s21
	s_cbranch_scc1 .Lre_entry
	s_branch .Lpl_entry
	s_add_i32 s56, s44, s66
	s_add_i32 s10, s42, s65
	s_and_b32 s55, s56, 0xffffffe0
	v_mov_b32_e32 v149, v139
	v_mov_b32_e32 v150, v140
	s_cmp_ge_i32 s55, s21
	s_cselect_b64 s[42:43], -1, 0
	v_add_u32_e32 v151, s10, v149
	v_lshlrev_b32_e32 v149, 3, v150
	v_mul_lo_u32 v152, v151, s79
	s_mov_b64 s[44:45], -1
	s_and_b64 vcc, exec, s[42:43]
	s_cbranch_vccz .LBB0_258
	v_add3_u32 v158, v149, s55, v152
	v_mov_b32_e32 v159, v0
	v_cvt_pk_bf16_f32 v154, v126, v127
	v_cvt_pk_bf16_f32 v155, v128, v129
	v_cvt_pk_bf16_f32 v156, v122, v123
	v_cvt_pk_bf16_f32 v157, v124, v125
	v_lshl_add_u64 v[158:159], v[158:159], 1, s[76:77]
	global_store_dwordx4 v[158:159], v[154:157], off
	s_mov_b64 s[44:45], 0

; __device__ __forceinline__ unsigned pk_bf16(float lo, float hi) { const f32x2 v = {lo, hi}; const bf16v2 b = __builtin_convertvector(v, bf16v2); return __builtin_bit_cast(unsigned, b); }
; #define GM_SCHED __builtin_amdgcn_sched_barrier(0)
; template <class Epi>
; __device__ __forceinline__ void gemm_phase(const bf16_t* __restrict__ A, const bf16_t* __restrict__ Bt, int M, int N, LAS unsigned char* lds, const Epi& epi, int vcu) {
;     ...
;         for (int ai = 0; ai < 2; ++ai)
; #pragma unroll
;             for (int mp = 0; mp < 2; ++mp) {
; #pragma unroll
;                 for (int mq = 0; mq < 2; ++mq)
; #pragma unroll
;                     for (int bj = 0; bj < 2; ++bj) { const int m = mp * 2 + mq;
;                         epi(brow + ai * HALF + wr * 64 + m * 16 + fre, (bcol + bj * HALF + wc * 32) >> 5, fqe, acc[ai][bj][m][0], acc[ai][bj][m][1]); }
;                 GM_SCHED;
;             }
;         }
;         if (!have_next) break;
;         brow = nrow; bcol = ncol;
;     __device__ __forceinline__ void operator()(int row, int G, int fq, f32x4 v0, f32x4 v1) const {
;     ...
;             u32x4 w; w.x = pk_bf16(v0[0], v0[1]); w.y = pk_bf16(v0[2], v0[3]); w.z = pk_bf16(v1[0], v1[1]); w.w = pk_bf16(v1[2], v1[3]);
;             *(u32x4*)(out + (ro + (unsigned)(col32 + 8 * fq))) = w;
.Lpl_entry:
	s_add_i32 s56, s44, s66
	s_add_i32 s11, s42, s65
	v_add_u32_e32 v149, s11, v139
	v_lshlrev_b32_e32 v212, 3, v140
	v_mul_lo_u32 v215, v149, s79
	v_add3_u32 v215, v215, s56, v212
	v_lshlrev_b32_e32 v215, 1, v215
	s_lshl_b32 s10, s79, 5
	s_mul_i32 s11, s10, 5
	s_mov_b64 s[42:43], s[76:77]
	v_cvt_pk_bf16_f32 v126, v126, v127
	v_cvt_pk_bf16_f32 v127, v128, v129
	v_cvt_pk_bf16_f32 v128, v122, v123
	v_cvt_pk_bf16_f32 v129, v124, v125
	global_store_dwordx4 v215, v[126:129], s[42:43]
	v_cvt_pk_bf16_f32 v118, v118, v119
	v_cvt_pk_bf16_f32 v119, v120, v121
	v_cvt_pk_bf16_f32 v120, v114, v115
	v_cvt_pk_bf16_f32 v121, v116, v117
	global_store_dwordx4 v215, v[118:121], s[42:43] offset:256
	s_add_u32 s42, s42, s10
	s_addc_u32 s43, s43, 0
	v_cvt_pk_bf16_f32 v110, v110, v111
	v_cvt_pk_bf16_f32 v111, v112, v113
	v_cvt_pk_bf16_f32 v112, v106, v107
	v_cvt_pk_bf16_f32 v113, v108, v109
	global_store_dwordx4 v215, v[110:113], s[42:43]
	v_cvt_pk_bf16_f32 v102, v102, v103
	v_cvt_pk_bf16_f32 v103, v104, v105
	v_cvt_pk_bf16_f32 v104, v98, v99
	v_cvt_pk_bf16_f32 v105, v100, v101
	global_store_dwordx4 v215, v[102:105], s[42:43] offset:256
	s_add_u32 s42, s42, s10
	s_addc_u32 s43, s43, 0
	v_cvt_pk_bf16_f32 v94, v94, v95
	v_cvt_pk_bf16_f32 v95, v96, v97
	v_cvt_pk_bf16_f32 v96, v90, v91
	v_cvt_pk_bf16_f32 v97, v92, v93
	global_store_dwordx4 v215, v[94:97], s[42:43]
	v_cvt_pk_bf16_f32 v86, v86, v87
	v_cvt_pk_bf16_f32 v87, v88, v89
	v_cvt_pk_bf16_f32 v88, v82, v83
	v_cvt_pk_bf16_f32 v89, v84, v85
	global_store_dwordx4 v215, v[86:89], s[42:43] offset:256
	s_add_u32 s42, s42, s10
	s_addc_u32 s43, s43, 0
	v_cvt_pk_bf16_f32 v78, v78, v79
	v_cvt_pk_bf16_f32 v79, v80, v81
	v_cvt_pk_bf16_f32 v80, v74, v75
	v_cvt_pk_bf16_f32 v81, v76, v77
	global_store_dwordx4 v215, v[78:81], s[42:43]
	v_cvt_pk_bf16_f32 v70, v70, v71
	v_cvt_pk_bf16_f32 v71, v72, v73
	v_cvt_pk_bf16_f32 v72, v66, v67
	v_cvt_pk_bf16_f32 v73, v68, v69
	global_store_dwordx4 v215, v[70:73], s[42:43] offset:256
	s_add_u32 s42, s42, s11
	s_addc_u32 s43, s43, 0
	v_cvt_pk_bf16_f32 v62, v62, v63
	v_cvt_pk_bf16_f32 v63, v64, v65
	v_cvt_pk_bf16_f32 v64, v58, v59
	v_cvt_pk_bf16_f32 v65, v60, v61
	global_store_dwordx4 v215, v[62:65], s[42:43]
	v_cvt_pk_bf16_f32 v54, v54, v55
	v_cvt_pk_bf16_f32 v55, v56, v57
	v_cvt_pk_bf16_f32 v56, v50, v51
	v_cvt_pk_bf16_f32 v57, v52, v53
	global_store_dwordx4 v215, v[54:57], s[42:43] offset:256
	s_add_u32 s42, s42, s10
	s_addc_u32 s43, s43, 0
	v_cvt_pk_bf16_f32 v46, v46, v47
	v_cvt_pk_bf16_f32 v47, v48, v49
	v_cvt_pk_bf16_f32 v48, v42, v43
	v_cvt_pk_bf16_f32 v49, v44, v45
	global_store_dwordx4 v215, v[46:49], s[42:43]
	v_cvt_pk_bf16_f32 v38, v38, v39
	v_cvt_pk_bf16_f32 v39, v40, v41
	v_cvt_pk_bf16_f32 v40, v34, v35
	v_cvt_pk_bf16_f32 v41, v36, v37
	global_store_dwordx4 v215, v[38:41], s[42:43] offset:256
	s_add_u32 s42, s42, s10
	s_addc_u32 s43, s43, 0
	v_cvt_pk_bf16_f32 v30, v30, v31
	v_cvt_pk_bf16_f32 v31, v32, v33
	v_cvt_pk_bf16_f32 v32, v26, v27
	v_cvt_pk_bf16_f32 v33, v28, v29
	global_store_dwordx4 v215, v[30:33], s[42:43]
	v_cvt_pk_bf16_f32 v22, v22, v23
	v_cvt_pk_bf16_f32 v23, v24, v25
	v_cvt_pk_bf16_f32 v24, v18, v19
	v_cvt_pk_bf16_f32 v25, v20, v21
	global_store_dwordx4 v215, v[22:25], s[42:43] offset:256
	s_add_u32 s42, s42, s10
	s_addc_u32 s43, s43, 0
	v_cvt_pk_bf16_f32 v14, v14, v15
	v_cvt_pk_bf16_f32 v15, v16, v17
	v_cvt_pk_bf16_f32 v16, v10, v11
	v_cvt_pk_bf16_f32 v17, v12, v13
	global_store_dwordx4 v215, v[14:17], s[42:43]
	v_cvt_pk_bf16_f32 v6, v6, v7
	v_cvt_pk_bf16_f32 v7, v8, v9
	v_cvt_pk_bf16_f32 v8, v2, v3
	v_cvt_pk_bf16_f32 v9, v4, v5
	global_store_dwordx4 v215, v[6:9], s[42:43] offset:256
	s_mov_b32 s83, s12
	s_mov_b32 s70, s13
	s_mov_b32 s36, s86
	s_mov_b32 s86, s87
	s_mov_b32 s87, s92
	s_mov_b64 s[12:13], s[72:73]
	s_mov_b32 s73, s93
	s_movk_i32 s72, 0x1fff
	s_branch .LBB0_251
